# diff attention: wave-uniform key-tile classification (near band / far left / far right) done with two scalar compares and SCC branches instead of the nine-instruction mask chain, far-bucket biases tak
# speedup vs baseline: 1.0042x; 1.0042x over previous
;     ...
;         { const int kq = st * 128;
;           const bool farR = (kq - q0w - 31 >= 91), farL = (kq + 63 - q0w <= -91), nr = !(farR || farL);
;           diff_step<true, false>(KA, VA, tab, qf, O, P, mrun, lrun, nr ? 0.f : (farR ? tab[256] : tab[0]), kq + ibq, kb0, kb1, vb0, vb1, nr, st == 0); }
.LBB0_202:
	s_add_i32 s37, s30, s29
	s_mov_b64 s[4:5], 0
	s_cmp_lt_i32 s29, s26
	s_cbranch_scc0 .Ldiff_far_a_hi
	s_cmpk_gt_i32 s37, 0xff66
	s_cbranch_scc0 .Ldiff_far_a_lo
	s_mov_b64 s[4:5], -1
	v_mov_b32_e32 v0, 0
	s_branch .LBB0_207
.Ldiff_far_a_hi:
	v_mov_b32_e32 v0, v255
	s_branch .LBB0_207
.Ldiff_far_a_lo:
	v_mov_b32_e32 v0, v254

;     ...
;         { const int kq = st * 128 + 64;
;           const bool farR = (kq - q0w - 31 >= 91), farL = (kq + 63 - q0w <= -91), nr = !(farR || farL);
;           diff_step<true, true>(KB, VA, tab, qf, O, P, mrun, lrun, nr ? 0.f : (farR ? tab[256] : tab[0]), kq + ibq, kb0, kb1, vb0, vb1, nr); }
.LBB0_214:
	s_mov_b64 s[4:5], 0
	s_cmp_lt_i32 s29, s28
	s_cbranch_scc0 .Ldiff_far_b_hi
	s_cmpk_gt_i32 s37, 0xff26
	s_cbranch_scc0 .Ldiff_far_b_lo
	s_mov_b64 s[4:5], -1
	v_mov_b32_e32 v4, 0
	s_branch .LBB0_220

;     ...
;         { const int kq = st * 128 + 64;
;           const bool farR = (kq - q0w - 31 >= 91), farL = (kq + 63 - q0w <= -91), nr = !(farR || farL);
;           diff_step<true, true>(KB, VA, tab, qf, O, P, mrun, lrun, nr ? 0.f : (farR ? tab[256] : tab[0]), kq + ibq, kb0, kb1, vb0, vb1, nr); }
.Ldiff_far_b_hi:
	v_mov_b32_e32 v4, v255
	s_branch .LBB0_220
.Ldiff_far_b_lo:
	v_mov_b32_e32 v4, v254
